# FFN2-down residual epilogue rewritten by hand: 2-3 row-groups of residual loads in flight with counted vmcnt waits; plus global_* ops and deferred SSQ atomics
# baseline (speedup 1.0000x reference)
; __device__ __forceinline__ int lane_asm() { int l; asm volatile("v_mbcnt_lo_u32_b32 %0, -1, 0\n\tv_mbcnt_hi_u32_b32 %0, -1, %0" : "=v"(l)); return l; }
;     __device__ __forceinline__ void operator()(const f32x4 (&acc)[2][2][4][2], const Unit& u, int wr, int wc, int fr_, int fq_) const {
;         const int l_ = lane_asm(); const int fr = l_ & 15, fq = l_ >> 4; (void)fr_; (void)fq_;
;         const int row0 = u.pm * BM + wr * 64 + fr, col0 = u.pn * BM + wc * 32 + 4 * fq;
;         f32x4 gv[2][2], gm[2][2];
; #pragma unroll
;         for (int bj = 0; bj < 2; ++bj)
; #pragma unroll
;             for (int n = 0; n < 2; ++n) { gv[bj][n] = *(const f32x4*)(gate + col0 + bj * HALF + n * 16);
;                 if constexpr (EMIT) gm[bj][n] = *(const f32x4*)(gmv + col0 + bj * HALF + n * 16); else gm[bj][n] = gv[bj][n]; }
; #pragma unroll
;         for (int ai = 0; ai < 2; ++ai)
; #pragma unroll
;         for (int mh = 0; mh < 2; ++mh) {
;             f32x4 bs[2][2][2];
; #pragma unroll
;             for (int m = 0; m < 2; ++m) { const size_t off = (size_t)(row0 + ai * HALF + (2 * mh + m) * 16) * ldc + col0;
; #pragma unroll
;                 for (int bj = 0; bj < 2; ++bj)
; #pragma unroll
;                     for (int n = 0; n < 2; ++n) bs[m][bj][n] = *(const f32x4*)(base + off + bj * HALF + n * 16); }
;             asm volatile("" ::: "memory");
; #pragma unroll
;             for (int m = 0; m < 2; ++m) { const int row = row0 + ai * HALF + (2 * mh + m) * 16; const size_t off = (size_t)row * ldc + col0; float ss = 0.f;
; #pragma unroll
;                 for (int bj = 0; bj < 2; ++bj)
; #pragma unroll
;                     for (int n = 0; n < 2; ++n) { const f32x4 o = bs[m][bj][n] + gv[bj][n] * acc[ai][bj][2 * mh + m][n]; *(f32x4*)(out + off + bj * HALF + n * 16) = o;
;                         if constexpr (EMIT) { ss += (o[0] * o[0] + o[1] * o[1]) + (o[2] * o[2] + o[3] * o[3]); const f32x4 y = o * gm[bj][n];
;                             typedef unsigned u32x2_t __attribute__((ext_vector_type(2))); u32x2_t w; w.x = cvt_pk_bf16(y[0], y[1]); w.y = cvt_pk_bf16(y[2], y[3]); *(u32x2_t*)(A2 + off + bj * HALF + n * 16) = w; } }
;                 if constexpr (EMIT) { ss += __shfl_xor(ss, 16); ss += __shfl_xor(ss, 32); if (fq == 0) atomicAdd(ssq + row, (unsigned long long)(ss * 16777216.0f)); } }
;             asm volatile("" ::: "memory");
;         }
.LBB0_1465:
	v_mbcnt_lo_u32_b32 v156, -1, 0
	v_mbcnt_hi_u32_b32 v156, -1, v156
	v_and_b32_e32 v157, 15, v156
	v_lshrrev_b32_e32 v158, 4, v156
	v_lshlrev_b32_e32 v157, 13, v157
	v_lshl_add_u32 v159, v158, 4, v157
	v_lshlrev_b32_e32 v160, 4, v158
	s_lshl_b32 s82, s54, 8
	s_add_i32 s82, s82, s45
	s_lshl_b32 s83, s55, 8
	s_add_i32 s83, s83, s46
	s_lshl_b32 s83, s83, 2
	s_add_u32 s74, s12, s83
	s_addc_u32 s75, s13, 0
	s_lshl_b32 s82, s82, 13
	s_add_u32 s82, s82, s83
	s_add_u32 s76, s6, s82
	s_addc_u32 s77, s7, 0
	s_add_u32 s78, s76, 0x20000
	s_addc_u32 s79, s77, 0
	s_add_u32 s84, s76, 0x40000
	s_addc_u32 s85, s77, 0
	s_add_u32 s86, s76, 0x60000
	s_addc_u32 s87, s77, 0
	s_add_u32 s88, s76, 0x100000
	s_addc_u32 s89, s77, 0
	s_add_u32 s90, s76, 0x120000
	s_addc_u32 s91, s77, 0
	s_add_u32 s94, s76, 0x140000
	s_addc_u32 s95, s77, 0
	s_add_u32 s96, s76, 0x160000
	s_addc_u32 s97, s77, 0
	global_load_dwordx4 v[140:143], v160, s[74:75]
	global_load_dwordx4 v[136:139], v160, s[74:75] offset:64
	global_load_dwordx4 v[132:135], v160, s[74:75] offset:512
	global_load_dwordx4 v[128:131], v160, s[74:75] offset:576
	global_load_dwordx4 v[166:169], v159, s[76:77]
	global_load_dwordx4 v[170:173], v159, s[76:77] offset:64
	global_load_dwordx4 v[174:177], v159, s[76:77] offset:512
	global_load_dwordx4 v[178:181], v159, s[76:77] offset:576
	global_load_dwordx4 v[182:185], v159, s[78:79]
	global_load_dwordx4 v[186:189], v159, s[78:79] offset:64
	global_load_dwordx4 v[190:193], v159, s[78:79] offset:512
	global_load_dwordx4 v[194:197], v159, s[78:79] offset:576
	global_load_dwordx4 v[218:221], v159, s[84:85]
	global_load_dwordx4 v[222:225], v159, s[84:85] offset:64
	global_load_dwordx4 v[226:229], v159, s[84:85] offset:512
	global_load_dwordx4 v[230:233], v159, s[84:85] offset:576
	global_load_dwordx4 v[234:237], v159, s[86:87]
	global_load_dwordx4 v[238:241], v159, s[86:87] offset:64
	global_load_dwordx4 v[242:245], v159, s[86:87] offset:512
	global_load_dwordx4 v[246:249], v159, s[86:87] offset:576
	s_waitcnt vmcnt(8)
	v_pk_fma_f32 v[126:127], v[126:127], v[142:143], v[168:169]
	v_pk_fma_f32 v[124:125], v[124:125], v[140:141], v[166:167]
	v_pk_fma_f32 v[122:123], v[122:123], v[138:139], v[172:173]
	v_pk_fma_f32 v[120:121], v[120:121], v[136:137], v[170:171]
	v_pk_fma_f32 v[110:111], v[110:111], v[134:135], v[176:177]
	v_pk_fma_f32 v[108:109], v[108:109], v[132:133], v[174:175]
	v_pk_fma_f32 v[106:107], v[106:107], v[130:131], v[180:181]
	v_pk_fma_f32 v[104:105], v[104:105], v[128:129], v[178:179]
	v_pk_fma_f32 v[118:119], v[118:119], v[142:143], v[184:185]
	v_pk_fma_f32 v[116:117], v[116:117], v[140:141], v[182:183]
	v_pk_fma_f32 v[114:115], v[114:115], v[138:139], v[188:189]
	v_pk_fma_f32 v[112:113], v[112:113], v[136:137], v[186:187]
	v_pk_fma_f32 v[102:103], v[102:103], v[134:135], v[192:193]
	v_pk_fma_f32 v[100:101], v[100:101], v[132:133], v[190:191]
	v_pk_fma_f32 v[98:99], v[98:99], v[130:131], v[196:197]
	v_pk_fma_f32 v[96:97], v[96:97], v[128:129], v[194:195]
	global_store_dwordx4 v159, v[124:127], s[76:77]
	global_store_dwordx4 v159, v[120:123], s[76:77] offset:64
	global_store_dwordx4 v159, v[108:111], s[76:77] offset:512
	global_store_dwordx4 v159, v[104:107], s[76:77] offset:576
	global_store_dwordx4 v159, v[116:119], s[78:79]
	global_store_dwordx4 v159, v[112:115], s[78:79] offset:64
	global_store_dwordx4 v159, v[100:103], s[78:79] offset:512
	global_store_dwordx4 v159, v[96:99], s[78:79] offset:576
	s_nop 1
	global_load_dwordx4 v[166:169], v159, s[88:89]
	global_load_dwordx4 v[170:173], v159, s[88:89] offset:64
	global_load_dwordx4 v[174:177], v159, s[88:89] offset:512
	global_load_dwordx4 v[178:181], v159, s[88:89] offset:576
	global_load_dwordx4 v[182:185], v159, s[90:91]
	global_load_dwordx4 v[186:189], v159, s[90:91] offset:64
	global_load_dwordx4 v[190:193], v159, s[90:91] offset:512
	global_load_dwordx4 v[194:197], v159, s[90:91] offset:576
	global_load_dwordx4 v[96:99], v159, s[94:95]
	global_load_dwordx4 v[100:103], v159, s[94:95] offset:64
	global_load_dwordx4 v[104:107], v159, s[94:95] offset:512
	global_load_dwordx4 v[108:111], v159, s[94:95] offset:576
	global_load_dwordx4 v[112:115], v159, s[96:97]
	global_load_dwordx4 v[116:119], v159, s[96:97] offset:64
	global_load_dwordx4 v[120:123], v159, s[96:97] offset:512
	global_load_dwordx4 v[124:127], v159, s[96:97] offset:576
	s_waitcnt vmcnt(24)
; __device__ __forceinline__ unsigned cvt_pk_bf16(float lo, float hi) { unsigned r; asm volatile("v_cvt_pk_bf16_f32 %0, %1, %2" : "=v"(r) : "v"(lo), "v"(hi)); return r; }
;     __device__ __forceinline__ void operator()(const f32x4 (&acc)[2][2][4][2], const Unit& u, int wr, int wc, int fr_, int fq_) const {
;     ...
;             for (int m = 0; m < 2; ++m) { const int row = row0 + ai * HALF + (2 * mh + m) * 16; const size_t off = (size_t)row * ldc + col0; float ss = 0.f;
; #pragma unroll
;                 for (int bj = 0; bj < 2; ++bj)
; #pragma unroll
;                     for (int n = 0; n < 2; ++n) { const f32x4 o = bs[m][bj][n] + gv[bj][n] * acc[ai][bj][2 * mh + m][n]; *(f32x4*)(out + off + bj * HALF + n * 16) = o;
;                         if constexpr (EMIT) { ss += (o[0] * o[0] + o[1] * o[1]) + (o[2] * o[2] + o[3] * o[3]); const f32x4 y = o * gm[bj][n];
;                             typedef unsigned u32x2_t __attribute__((ext_vector_type(2))); u32x2_t w; w.x = cvt_pk_bf16(y[0], y[1]); w.y = cvt_pk_bf16(y[2], y[3]); *(u32x2_t*)(A2 + off + bj * HALF + n * 16) = w; } }
;                 if constexpr (EMIT) { ss += __shfl_xor(ss, 16); ss += __shfl_xor(ss, 32); if (fq == 0) atomicAdd(ssq + row, (unsigned long long)(ss * 16777216.0f)); } }
;             asm volatile("" ::: "memory");
;         }
	v_pk_fma_f32 v[94:95], v[94:95], v[142:143], v[220:221]
	v_pk_fma_f32 v[92:93], v[92:93], v[140:141], v[218:219]
	v_pk_fma_f32 v[90:91], v[90:91], v[138:139], v[224:225]
	v_pk_fma_f32 v[88:89], v[88:89], v[136:137], v[222:223]
	v_pk_fma_f32 v[78:79], v[78:79], v[134:135], v[228:229]
	v_pk_fma_f32 v[76:77], v[76:77], v[132:133], v[226:227]
	v_pk_fma_f32 v[74:75], v[74:75], v[130:131], v[232:233]
	v_pk_fma_f32 v[72:73], v[72:73], v[128:129], v[230:231]
	v_pk_fma_f32 v[86:87], v[86:87], v[142:143], v[236:237]
	v_pk_fma_f32 v[84:85], v[84:85], v[140:141], v[234:235]
	v_pk_fma_f32 v[82:83], v[82:83], v[138:139], v[240:241]
	v_pk_fma_f32 v[80:81], v[80:81], v[136:137], v[238:239]
	v_pk_fma_f32 v[70:71], v[70:71], v[134:135], v[244:245]
	v_pk_fma_f32 v[68:69], v[68:69], v[132:133], v[242:243]
	v_pk_fma_f32 v[66:67], v[66:67], v[130:131], v[248:249]
	v_pk_fma_f32 v[64:65], v[64:65], v[128:129], v[246:247]
	global_store_dwordx4 v159, v[92:95], s[84:85]
	global_store_dwordx4 v159, v[88:91], s[84:85] offset:64
	global_store_dwordx4 v159, v[76:79], s[84:85] offset:512
	global_store_dwordx4 v159, v[72:75], s[84:85] offset:576
	global_store_dwordx4 v159, v[84:87], s[86:87]
	global_store_dwordx4 v159, v[80:83], s[86:87] offset:64
	global_store_dwordx4 v159, v[68:71], s[86:87] offset:512
	global_store_dwordx4 v159, v[64:67], s[86:87] offset:576
	s_waitcnt vmcnt(16)
	v_pk_fma_f32 v[62:63], v[62:63], v[142:143], v[168:169]
	v_pk_fma_f32 v[60:61], v[60:61], v[140:141], v[166:167]
	v_pk_fma_f32 v[58:59], v[58:59], v[138:139], v[172:173]
	v_pk_fma_f32 v[56:57], v[56:57], v[136:137], v[170:171]
	v_pk_fma_f32 v[46:47], v[46:47], v[134:135], v[176:177]
	v_pk_fma_f32 v[44:45], v[44:45], v[132:133], v[174:175]
	v_pk_fma_f32 v[42:43], v[42:43], v[130:131], v[180:181]
	v_pk_fma_f32 v[40:41], v[40:41], v[128:129], v[178:179]
	v_pk_fma_f32 v[54:55], v[54:55], v[142:143], v[184:185]
	v_pk_fma_f32 v[52:53], v[52:53], v[140:141], v[182:183]
	v_pk_fma_f32 v[50:51], v[50:51], v[138:139], v[188:189]
	v_pk_fma_f32 v[48:49], v[48:49], v[136:137], v[186:187]
	v_pk_fma_f32 v[38:39], v[38:39], v[134:135], v[192:193]
	v_pk_fma_f32 v[36:37], v[36:37], v[132:133], v[190:191]
	v_pk_fma_f32 v[34:35], v[34:35], v[130:131], v[196:197]
	v_pk_fma_f32 v[32:33], v[32:33], v[128:129], v[194:195]
	global_store_dwordx4 v159, v[60:63], s[88:89]
	global_store_dwordx4 v159, v[56:59], s[88:89] offset:64
	global_store_dwordx4 v159, v[44:47], s[88:89] offset:512
	global_store_dwordx4 v159, v[40:43], s[88:89] offset:576
	global_store_dwordx4 v159, v[52:55], s[90:91]
	global_store_dwordx4 v159, v[48:51], s[90:91] offset:64
	global_store_dwordx4 v159, v[36:39], s[90:91] offset:512
	global_store_dwordx4 v159, v[32:35], s[90:91] offset:576
	s_waitcnt vmcnt(16)
	v_pk_fma_f32 v[30:31], v[30:31], v[142:143], v[98:99]
	v_pk_fma_f32 v[28:29], v[28:29], v[140:141], v[96:97]
	v_pk_fma_f32 v[26:27], v[26:27], v[138:139], v[102:103]
	v_pk_fma_f32 v[24:25], v[24:25], v[136:137], v[100:101]
	v_pk_fma_f32 v[14:15], v[14:15], v[134:135], v[106:107]
	v_pk_fma_f32 v[12:13], v[12:13], v[132:133], v[104:105]
	v_pk_fma_f32 v[10:11], v[10:11], v[130:131], v[110:111]
	v_pk_fma_f32 v[8:9], v[8:9], v[128:129], v[108:109]
	v_pk_fma_f32 v[22:23], v[22:23], v[142:143], v[114:115]
	v_pk_fma_f32 v[20:21], v[20:21], v[140:141], v[112:113]
	v_pk_fma_f32 v[18:19], v[18:19], v[138:139], v[118:119]
	v_pk_fma_f32 v[16:17], v[16:17], v[136:137], v[116:117]
	v_pk_fma_f32 v[6:7], v[6:7], v[134:135], v[122:123]
	v_pk_fma_f32 v[4:5], v[4:5], v[132:133], v[120:121]
	v_pk_fma_f32 v[2:3], v[2:3], v[130:131], v[126:127]
	v_pk_fma_f32 v[0:1], v[0:1], v[128:129], v[124:125]
	global_store_dwordx4 v159, v[28:31], s[94:95]
	global_store_dwordx4 v159, v[24:27], s[94:95] offset:64
	global_store_dwordx4 v159, v[12:15], s[94:95] offset:512
	global_store_dwordx4 v159, v[8:11], s[94:95] offset:576
	global_store_dwordx4 v159, v[20:23], s[96:97]
	global_store_dwordx4 v159, v[16:19], s[96:97] offset:64
	global_store_dwordx4 v159, v[4:7], s[96:97] offset:512
	global_store_dwordx4 v159, v[0:3], s[96:97] offset:576
	s_and_b64 vcc, exec, s[0:1]
	s_mov_b64 s[0:1], -1
	s_cbranch_vccnz .LBB0_1450
	s_andn2_b64 vcc, exec, s[10:11]
	s_cbranch_vccnz .LBB0_1449
	s_barrier
	s_branch .LBB0_1449
